# combo6: combo5 + layer-0 norm loop: prefetched row waited only at the latch with counted vmcnt(3); bias loads drained once before the loop
# speedup vs baseline: 1.0147x; 1.0095x over previous
; template <bool FG, bool BIN = false> __device__ __forceinline__ void norm_phase(const float* hin, const float* gain, bf16_t* out, const float* win, const float* fbias, float* logf, int gw, int NGW, int lane) {
;     float g[16];
; #pragma unroll
;     for (int i = 0; i < 2; ++i) { const int c0 = 8 * (lane + 64 * i); const f32x4 a = *(const f32x4*)(gain + c0), b = *(const f32x4*)(gain + c0 + 4);
;         g[8 * i + 0] = a[0]; g[8 * i + 1] = a[1]; g[8 * i + 2] = a[2]; g[8 * i + 3] = a[3]; g[8 * i + 4] = b[0]; g[8 * i + 5] = b[1]; g[8 * i + 6] = b[2]; g[8 * i + 7] = b[3]; }
;     float wf[6][16]; float fb[6];
;     if (FG) {
; #pragma unroll
;         for (int i = 0; i < 2; ++i)
; #pragma unroll
;             for (int e = 0; e < 8; ++e) { const float* wp = win + (size_t)(8 * (lane + 64 * i) + e) * INC + 2432;
; #pragma unroll
;                 for (int j = 0; j < 6; ++j) wf[j][8 * i + e] = wp[j] * g[8 * i + e]; }
; #pragma unroll
;         for (int j = 0; j < 6; ++j) fb[j] = fbias[j];
;     }
.LBB0_167:
	s_or_b64 exec, exec, s[0:1]
	s_mov_b32 s0, -1
	s_mov_b32 s20, s48
	v_mbcnt_lo_u32_b32 v2, s0, 0
	v_mbcnt_hi_u32_b32 v22, s0, v2
	s_mov_b64 s[0:1], s[46:47]
	s_mov_b64 s[6:7], s[46:47]
	s_mov_b64 s[10:11], s[46:47]
	s_mov_b64 s[8:9], s[46:47]
	s_mov_b64 s[12:13], s[46:47]
	s_mov_b64 s[4:5], s[46:47]
	s_cmpk_gt_i32 s20, 0x7fff
	s_mul_hi_i32 s41, s58, 24
	s_mul_i32 s40, s58, 24
	s_cbranch_scc1 .LBB0_174
	s_load_dwordx2 s[2:3], s[6:7], 0x10
	s_load_dwordx2 s[14:15], s[8:9], 0x18
	v_lshlrev_b32_e32 v26, 3, v22
	v_ashrrev_i32_e32 v27, 31, v26
	v_lshlrev_b64 v[24:25], 2, v[26:27]
	s_waitcnt lgkmcnt(0)
	v_lshl_add_u64 v[20:21], s[2:3], 0, v[24:25]
	s_movk_i32 s2, 0x3818
	v_mov_b64_e32 v[18:19], s[14:15]
	v_mad_i64_i32 v[6:7], s[6:7], v26, s2, v[18:19]
	s_mov_b64 s[8:9], 0x2600
	s_movk_i32 s3, 0x2000
	v_lshl_add_u64 v[8:9], v[6:7], 0, s[8:9]
	v_add_co_u32_e32 v6, vcc, s3, v6
	global_load_dwordx4 v[2:5], v[20:21], off
	s_nop 0
	v_addc_co_u32_e32 v7, vcc, 0, v7, vcc
	global_load_dwordx4 v[28:31], v[6:7], off offset:1536
	global_load_dwordx2 v[44:45], v[8:9], off offset:16
	v_or_b32_e32 v6, 1, v26
	v_mad_i64_i32 v[6:7], s[6:7], v6, s2, v[18:19]
	v_lshl_add_u64 v[8:9], v[6:7], 0, s[8:9]
	v_add_co_u32_e32 v6, vcc, s3, v6
	v_or_b32_e32 v52, 4, v26
	s_nop 0
	v_addc_co_u32_e32 v7, vcc, 0, v7, vcc
	global_load_dwordx4 v[32:35], v[6:7], off offset:1536
	global_load_dwordx2 v[46:47], v[8:9], off offset:16
	v_or_b32_e32 v6, 2, v26
	v_mad_i64_i32 v[6:7], s[6:7], v6, s2, v[18:19]
	v_lshl_add_u64 v[8:9], v[6:7], 0, s[8:9]
	v_add_co_u32_e32 v6, vcc, s3, v6
	v_add_u32_e32 v54, 0x200, v26
	s_nop 0
	v_addc_co_u32_e32 v7, vcc, 0, v7, vcc
	global_load_dwordx4 v[36:39], v[6:7], off offset:1536
	global_load_dwordx2 v[48:49], v[8:9], off offset:16
	v_or_b32_e32 v6, 3, v26
	v_mad_i64_i32 v[6:7], s[6:7], v6, s2, v[18:19]
	v_add_co_u32_e32 v8, vcc, s3, v6
	v_lshl_add_u64 v[10:11], v[6:7], 0, s[8:9]
	s_nop 0
	v_addc_co_u32_e32 v9, vcc, 0, v7, vcc
	global_load_dwordx4 v[40:43], v[8:9], off offset:1536
	global_load_dwordx2 v[50:51], v[10:11], off offset:16
	s_nop 0
	global_load_dwordx4 v[6:9], v[20:21], off offset:16
	s_load_dwordx2 s[24:25], s[0:1], 0x0
	s_load_dwordx2 s[22:23], s[10:11], 0x98
	s_load_dwordx2 s[6:7], s[12:13], 0x38
	global_load_dwordx4 v[10:13], v[20:21], off offset:2064
	global_load_dwordx4 v[14:17], v[20:21], off offset:2048
	v_mad_i64_i32 v[20:21], s[0:1], v52, s2, v[18:19]
	v_lshl_add_u64 v[52:53], v[20:21], 0, s[8:9]
	v_add_co_u32_e32 v20, vcc, s3, v20
	s_ashr_i32 s21, s20, 31
	s_nop 0
	v_addc_co_u32_e32 v21, vcc, 0, v21, vcc
	v_mov_b32_e32 v23, 0
	v_cmp_eq_u32_e64 s[10:11], 2, v22
	v_cmp_eq_u32_e64 s[12:13], 3, v22
	v_cmp_eq_u32_e64 s[14:15], 4, v22
	v_cmp_eq_u32_e64 s[16:17], 5, v22
	v_mov_b32_e32 v161, 0x358637bd
	s_mov_b32 s28, 0xc2b17218
	s_mov_b32 s29, 0x7f800000
	s_mov_b32 s30, 0x3f2aaaab
	v_mov_b32_e32 v162, 0x3ecc95a3
	s_mov_b32 s31, 0x3f317218
	s_mov_b32 s33, 0x33800000
	v_mov_b32_e32 v163, 0x7f800000
	s_waitcnt vmcnt(10)
	v_mul_f32_e32 v65, v2, v28
	v_mul_f32_e32 v66, v2, v29
	v_mul_f32_e32 v67, v2, v30
	v_mul_f32_e32 v68, v2, v31
	global_load_dwordx4 v[28:31], v[20:21], off offset:1536
	global_load_dwordx2 v[94:95], v[52:53], off offset:16
	v_or_b32_e32 v20, 5, v26
	v_mad_i64_i32 v[20:21], s[0:1], v20, s2, v[18:19]
	s_waitcnt vmcnt(11)
	v_mul_f32_e32 v69, v2, v44
	v_mul_f32_e32 v70, v2, v45
	s_waitcnt vmcnt(10)
	v_mul_f32_e32 v71, v3, v32
	v_mul_f32_e32 v72, v3, v33
	v_mul_f32_e32 v73, v3, v34
	v_mul_f32_e32 v74, v3, v35
	s_waitcnt vmcnt(9)
	v_mul_f32_e32 v75, v3, v46
	v_mul_f32_e32 v76, v3, v47
	s_waitcnt vmcnt(8)
	v_mul_f32_e32 v77, v4, v36
	v_mul_f32_e32 v78, v4, v37
	v_lshl_add_u64 v[36:37], v[20:21], 0, s[8:9]
	v_add_co_u32_e32 v20, vcc, s3, v20
	v_mul_f32_e32 v79, v4, v38
	s_nop 0
	v_addc_co_u32_e32 v21, vcc, 0, v21, vcc
	global_load_dwordx4 v[32:35], v[20:21], off offset:1536
	global_load_dwordx2 v[100:101], v[36:37], off offset:16
	v_or_b32_e32 v20, 6, v26
	v_mad_i64_i32 v[20:21], s[0:1], v20, s2, v[18:19]
	s_waitcnt vmcnt(8)
	v_mul_f32_e32 v83, v5, v40
	v_mul_f32_e32 v84, v5, v41
	v_lshl_add_u64 v[40:41], v[20:21], 0, s[8:9]
	v_add_co_u32_e32 v20, vcc, s3, v20
	v_mul_f32_e32 v80, v4, v39
	s_nop 0
	v_addc_co_u32_e32 v21, vcc, 0, v21, vcc
	global_load_dwordx4 v[36:39], v[20:21], off offset:1536
	global_load_dwordx2 v[106:107], v[40:41], off offset:16
	v_or_b32_e32 v20, 7, v26
	v_mad_i64_i32 v[20:21], s[0:1], v20, s2, v[18:19]
	v_lshl_add_u64 v[44:45], v[20:21], 0, s[8:9]
	v_add_co_u32_e32 v20, vcc, s3, v20
	v_mul_f32_e32 v85, v5, v42
	s_nop 0
	v_addc_co_u32_e32 v21, vcc, 0, v21, vcc
	v_mul_f32_e32 v86, v5, v43
	global_load_dwordx4 v[40:43], v[20:21], off offset:1536
	global_load_dwordx2 v[112:113], v[44:45], off offset:16
	v_mad_i64_i32 v[20:21], s[0:1], v54, s2, v[18:19]
	v_mul_f32_e32 v81, v4, v48
	v_mul_f32_e32 v82, v4, v49
	v_lshl_add_u64 v[48:49], v[20:21], 0, s[8:9]
	v_add_co_u32_e32 v20, vcc, s3, v20
	s_waitcnt vmcnt(11)
	v_mul_f32_e32 v87, v5, v50
	v_addc_co_u32_e32 v21, vcc, 0, v21, vcc
	global_load_dwordx4 v[44:47], v[20:21], off offset:1536
	global_load_dwordx2 v[118:119], v[48:49], off offset:16
	v_add_u32_e32 v20, 0x201, v26
	v_mad_i64_i32 v[20:21], s[0:1], v20, s2, v[18:19]
	v_lshl_add_u64 v[52:53], v[20:21], 0, s[8:9]
	v_add_co_u32_e32 v20, vcc, s3, v20
	v_mul_f32_e32 v88, v5, v51
	s_nop 0
	v_addc_co_u32_e32 v21, vcc, 0, v21, vcc
	global_load_dwordx4 v[48:51], v[20:21], off offset:1536
	global_load_dwordx2 v[124:125], v[52:53], off offset:16
	v_add_u32_e32 v20, 0x202, v26
	v_mad_i64_i32 v[20:21], s[0:1], v20, s2, v[18:19]
	v_lshl_add_u64 v[56:57], v[20:21], 0, s[8:9]
	v_add_co_u32_e32 v20, vcc, s3, v20
	s_waitcnt vmcnt(11)
; template <bool FG, bool BIN = false> __device__ __forceinline__ void norm_phase(const float* hin, const float* gain, bf16_t* out, const float* win, const float* fbias, float* logf, int gw, int NGW, int lane) {
;     ...
;         for (int j = 0; j < 6; ++j) fb[j] = fbias[j];
;     ...
;     f32x4 nx[4];
;     const bf16_t* hbin = (const bf16_t*)hin;
;     ...
;     if (gw < T) NORM_LD(gw);
;     for (int row = gw; row < T; row += NGW) {
;         float x[16];
; #pragma unroll
;         for (int i = 0; i < 4; ++i) { x[4 * i + 0] = nx[i][0]; x[4 * i + 1] = nx[i][1]; x[4 * i + 2] = nx[i][2]; x[4 * i + 3] = nx[i][3]; }
;         if (row + NGW < T) NORM_LD(row + NGW);
	v_mul_f32_e32 v89, v6, v28
	v_addc_co_u32_e32 v21, vcc, 0, v21, vcc
	global_load_dwordx4 v[52:55], v[20:21], off offset:1536
	global_load_dwordx2 v[130:131], v[56:57], off offset:16
	v_add_u32_e32 v20, 0x203, v26
	v_mad_i64_i32 v[20:21], s[0:1], v20, s2, v[18:19]
	v_lshl_add_u64 v[60:61], v[20:21], 0, s[8:9]
	v_add_co_u32_e32 v20, vcc, s3, v20
	v_mul_f32_e32 v92, v6, v31
	s_nop 0
	v_addc_co_u32_e32 v21, vcc, 0, v21, vcc
	global_load_dwordx4 v[56:59], v[20:21], off offset:1536
	global_load_dwordx2 v[136:137], v[60:61], off offset:16
	v_add_u32_e32 v20, 0x204, v26
	v_mad_i64_i32 v[20:21], s[0:1], v20, s2, v[18:19]
	v_lshl_add_u64 v[90:91], v[20:21], 0, s[8:9]
	v_add_co_u32_e32 v20, vcc, s3, v20
	s_waitcnt vmcnt(14)
	v_mul_f32_e32 v93, v6, v94
	v_addc_co_u32_e32 v21, vcc, 0, v21, vcc
	global_load_dwordx4 v[60:63], v[20:21], off offset:1536
	global_load_dwordx2 v[142:143], v[90:91], off offset:16
	v_add_u32_e32 v20, 0x205, v26
	v_mad_i64_i32 v[20:21], s[0:1], v20, s2, v[18:19]
	v_lshl_add_u64 v[90:91], v[20:21], 0, s[8:9]
	v_add_co_u32_e32 v20, vcc, s3, v20
	v_mul_f32_e32 v94, v6, v95
	s_nop 0
	v_addc_co_u32_e32 v21, vcc, 0, v21, vcc
	global_load_dwordx4 v[144:147], v[20:21], off offset:1536
	global_load_dwordx2 v[148:149], v[90:91], off offset:16
	v_add_u32_e32 v20, 0x206, v26
	v_mad_i64_i32 v[20:21], s[0:1], v20, s2, v[18:19]
	v_lshl_add_u64 v[90:91], v[20:21], 0, s[8:9]
	v_add_co_u32_e32 v20, vcc, s3, v20
	s_waitcnt vmcnt(15)
	v_mul_f32_e32 v103, v8, v38
	v_addc_co_u32_e32 v21, vcc, 0, v21, vcc
	global_load_dwordx4 v[150:153], v[20:21], off offset:1536
	global_load_dwordx2 v[154:155], v[90:91], off offset:16
	v_add_u32_e32 v20, 0x207, v26
	v_mad_i64_i32 v[18:19], s[0:1], v20, s2, v[18:19]
	v_add_co_u32_e32 v20, vcc, s3, v18
	s_lshl_b64 s[0:1], s[20:21], 12
	s_nop 0
	v_addc_co_u32_e32 v21, vcc, 0, v19, vcc
	v_lshl_add_u64 v[18:19], v[18:19], 0, s[8:9]
	s_waitcnt lgkmcnt(0)
	s_add_u32 s0, s24, s0
	global_load_dwordx4 v[156:159], v[20:21], off offset:1536
	v_mul_f32_e32 v90, v6, v29
	global_load_dwordx2 v[28:29], v[18:19], off offset:16
	s_addc_u32 s1, s25, s1
	v_lshl_add_u64 v[18:19], s[0:1], 0, v[24:25]
	v_mul_f32_e32 v104, v8, v39
	s_waitcnt vmcnt(18)
	v_mul_f32_e32 v105, v8, v106
	v_mul_f32_e32 v106, v8, v107
	s_waitcnt vmcnt(17)
	v_mul_f32_e32 v107, v9, v40
	v_mul_f32_e32 v108, v9, v41
	v_mul_f32_e32 v109, v9, v42
	v_mul_f32_e32 v110, v9, v43
	s_waitcnt vmcnt(16)
	v_mul_f32_e32 v111, v9, v112
	v_mul_f32_e32 v112, v9, v113
	s_waitcnt vmcnt(15)
	v_mul_f32_e32 v113, v14, v44
	v_mul_f32_e32 v114, v14, v45
	v_mul_f32_e32 v115, v14, v46
	v_mul_f32_e32 v116, v14, v47
	s_waitcnt vmcnt(14)
	v_mul_f32_e32 v117, v14, v118
	v_mul_f32_e32 v118, v14, v119
	s_waitcnt vmcnt(13)
	v_mul_f32_e32 v119, v15, v48
	v_mul_f32_e32 v120, v15, v49
	v_mul_f32_e32 v121, v15, v50
	v_mul_f32_e32 v122, v15, v51
	s_waitcnt vmcnt(12)
	v_mul_f32_e32 v123, v15, v124
	v_mul_f32_e32 v124, v15, v125
	s_mul_i32 s3, s20, 24
	s_mul_hi_i32 s2, s20, 24
	s_waitcnt vmcnt(11)
	v_mul_f32_e32 v125, v16, v52
	v_mul_f32_e32 v126, v16, v53
	v_mul_f32_e32 v127, v16, v54
	v_mul_f32_e32 v128, v16, v55
	global_load_dwordx4 v[38:41], v[18:19], off offset:2064
	global_load_dwordx4 v[42:45], v[18:19], off offset:2048
	global_load_dwordx4 v[46:49], v[18:19], off offset:16
	global_load_dwordx4 v[50:53], v[18:19], off
	s_nop 0
	global_load_dwordx4 v[18:21], v23, s[6:7]
	global_load_dwordx2 v[54:55], v23, s[6:7] offset:16
	s_load_dwordx2 s[0:1], s[4:5], 0x98
	v_ashrrev_i32_e32 v23, 31, v22
	v_cmp_gt_i32_e64 s[4:5], 6, v22
	v_cmp_eq_u32_e64 s[6:7], 0, v22
	v_cmp_eq_u32_e64 s[8:9], 1, v22
	s_waitcnt lgkmcnt(0)
	s_add_u32 s0, s0, s3
	s_addc_u32 s1, s1, s2
	v_lshl_add_u64 v[22:23], v[22:23], 2, s[0:1]
	s_mov_b64 s[0:1], 0x17804000
	s_waitcnt vmcnt(16)
	v_mul_f32_e32 v129, v16, v130
	v_mul_f32_e32 v130, v16, v131
	s_waitcnt vmcnt(15)
	v_mul_f32_e32 v131, v17, v56
	v_mul_f32_e32 v132, v17, v57
	v_lshl_add_u64 v[56:57], v[22:23], 0, s[0:1]
	s_ashr_i32 s59, s58, 31
	s_lshl_b64 s[0:1], s[20:21], 11
	s_add_u32 s0, s22, s0
	s_addc_u32 s1, s23, s1
	v_lshl_add_u64 v[22:23], v[26:27], 1, s[0:1]
	s_mov_b64 s[0:1], 0x5804000
	v_mul_f32_e32 v133, v17, v58
	v_mul_f32_e32 v134, v17, v59
	v_lshl_add_u64 v[58:59], v[22:23], 0, s[0:1]
	s_add_i32 s0, s20, s58
	s_ashr_i32 s1, s0, 31
	s_lshl_b64 s[22:23], s[58:59], 11
	s_lshl_b64 s[0:1], s[0:1], 12
	s_add_u32 s0, s24, s0
	s_addc_u32 s1, s25, s1
	v_lshl_add_u64 v[22:23], s[0:1], 0, v[24:25]
	s_mov_b64 s[0:1], 0x810
	s_waitcnt vmcnt(14)
	v_mul_f32_e32 v135, v17, v136
	v_mul_f32_e32 v136, v17, v137
	s_waitcnt vmcnt(13)
	v_mul_f32_e32 v137, v10, v60
	v_mul_f32_e32 v138, v10, v61
	v_lshl_add_u64 v[60:61], v[22:23], 0, s[0:1]
	v_mul_f32_e32 v91, v6, v30
	v_mul_f32_e32 v95, v7, v32
	v_mul_f32_e32 v96, v7, v33
	v_mul_f32_e32 v97, v7, v34
	v_mul_f32_e32 v98, v7, v35
	v_mul_f32_e32 v99, v7, v100
	v_mul_f32_e32 v100, v7, v101
	v_mul_f32_e32 v101, v8, v36
	v_mul_f32_e32 v102, v8, v37
	s_waitcnt vmcnt(12)
	v_mul_f32_e32 v141, v10, v142
	v_mul_f32_e32 v142, v10, v143
	s_waitcnt vmcnt(11)
	v_mul_f32_e32 v143, v11, v144
	v_mul_f32_e32 v144, v11, v145
	v_mul_f32_e32 v145, v11, v146
	v_mul_f32_e32 v146, v11, v147
	s_waitcnt vmcnt(10)
	v_mul_f32_e32 v147, v11, v148
	v_mul_f32_e32 v148, v11, v149
	s_waitcnt vmcnt(9)
	v_mul_f32_e32 v149, v12, v150
	v_mul_f32_e32 v150, v12, v151
	v_mul_f32_e32 v151, v12, v152
	v_mul_f32_e32 v152, v12, v153
	s_waitcnt vmcnt(8)
	v_mul_f32_e32 v153, v12, v154
	v_mul_f32_e32 v154, v12, v155
	s_waitcnt vmcnt(7)
	v_mul_f32_e32 v155, v13, v156
	v_mul_f32_e32 v156, v13, v157
	v_mul_f32_e32 v157, v13, v158
	v_mul_f32_e32 v158, v13, v159
	s_waitcnt vmcnt(6)
	v_mul_f32_e32 v159, v13, v28
	v_mul_f32_e32 v160, v13, v29
	v_mul_f32_e32 v139, v10, v62
	v_mul_f32_e32 v140, v10, v63
	s_lshl_b64 s[24:25], s[58:59], 12
	s_mov_b32 s2, 0xbfb8aa3b
	s_mov_b32 s3, 0xb2a5705f
	s_mov_b32 s21, 0x42ce8ed0
	v_mov_b32_e32 v62, 0x3f317218
	s_waitcnt vmcnt(5)
	v_mov_b64_e32 v[30:31], v[38:39]
	s_waitcnt vmcnt(4)
	v_mov_b64_e32 v[34:35], v[42:43]
	s_waitcnt vmcnt(3)
	v_mov_b64_e32 v[22:23], v[46:47]
	s_waitcnt vmcnt(2)
	v_mov_b64_e32 v[26:27], v[50:51]
	v_mov_b64_e32 v[32:33], v[40:41]
	v_mov_b64_e32 v[36:37], v[44:45]
	v_mov_b64_e32 v[24:25], v[48:49]
	v_mov_b64_e32 v[28:29], v[52:53]
	s_waitcnt vmcnt(0)
	s_branch .LBB0_170
.LBB0_169:
	s_or_b64 exec, exec, s[0:1]
	s_waitcnt vmcnt(3)
	v_mov_b64_e32 v[40:41], v[32:33]
	s_waitcnt vmcnt(3)
	v_mov_b64_e32 v[44:45], v[36:37]
	v_mov_b64_e32 v[48:49], v[24:25]
	v_mov_b64_e32 v[52:53], v[28:29]
	v_lshl_add_u64 v[56:57], v[56:57], 0, s[40:41]
	v_lshl_add_u64 v[58:59], v[58:59], 0, s[22:23]
	v_lshl_add_u64 v[60:61], v[60:61], 0, s[24:25]
	s_andn2_b64 vcc, exec, s[26:27]
	v_mov_b64_e32 v[38:39], v[30:31]
	v_mov_b64_e32 v[42:43], v[34:35]
	v_mov_b64_e32 v[46:47], v[22:23]
	v_mov_b64_e32 v[50:51], v[26:27]
	s_cbranch_vccz .LBB0_174

; __device__ __forceinline__ unsigned pk2(float lo, float hi) { f32x2_t v = {lo, hi}; bf16x2_t b = __builtin_convertvector(v, bf16x2_t); return __builtin_bit_cast(unsigned, b); }
; __device__ __forceinline__ float wave_sum(float v) { return xor32_sum(xor16_sum(row16_sum(v))); }
; __device__ __forceinline__ float fast_rsq(float x) { return __builtin_amdgcn_rsqf(x); }
; template <bool FG, bool BIN = false> __device__ __forceinline__ void norm_phase(const float* hin, const float* gain, bf16_t* out, const float* win, const float* fbias, float* logf, int gw, int NGW, int lane) {
;     ...
;         float x[16];
; #pragma unroll
;         for (int i = 0; i < 4; ++i) { x[4 * i + 0] = nx[i][0]; x[4 * i + 1] = nx[i][1]; x[4 * i + 2] = nx[i][2]; x[4 * i + 3] = nx[i][3]; }
;         if (row + NGW < T) NORM_LD(row + NGW);
;         float ss = 0.f;
; #pragma unroll
;         for (int e = 0; e < 16; ++e) ss += x[e] * x[e];
;         ss = wave_sum(ss);
;         const float rstd = fast_rsq(ss * (1.0f / DM) + EPS);
; #pragma unroll
;         for (int i = 0; i < 2; ++i) { u32x4 w;
;             w.x = pk2(x[8 * i + 0] * rstd * g[8 * i + 0], x[8 * i + 1] * rstd * g[8 * i + 1]); w.y = pk2(x[8 * i + 2] * rstd * g[8 * i + 2], x[8 * i + 3] * rstd * g[8 * i + 3]);
;             w.z = pk2(x[8 * i + 4] * rstd * g[8 * i + 4], x[8 * i + 5] * rstd * g[8 * i + 5]); w.w = pk2(x[8 * i + 6] * rstd * g[8 * i + 6], x[8 * i + 7] * rstd * g[8 * i + 7]);
;             *(u32x4*)(out + (size_t)row * DM + 8 * (lane + 64 * i)) = w; }
;         if (FG) {
;             float mine = 0.f;
; #pragma unroll
;             for (int j = 0; j < 6; ++j) { float d = 0.f;
; #pragma unroll
;                 for (int e = 0; e < 16; ++e) d += x[e] * wf[j][e];
;                 d = wave_sum(d) * rstd + fb[j];
.LBB0_172:
	v_mul_f32_e32 v63, v51, v51
	v_fmac_f32_e32 v63, v50, v50
	v_fmac_f32_e32 v63, v52, v52
	v_fmac_f32_e32 v63, v53, v53
	v_fmac_f32_e32 v63, v46, v46
	v_fmac_f32_e32 v63, v47, v47
	v_fmac_f32_e32 v63, v48, v48
	v_fmac_f32_e32 v63, v49, v49
	v_fmac_f32_e32 v63, v42, v42
	v_fmac_f32_e32 v63, v43, v43
	v_fmac_f32_e32 v63, v44, v44
	v_fmac_f32_e32 v63, v45, v45
	v_fmac_f32_e32 v63, v38, v38
	v_fmac_f32_e32 v63, v39, v39
	v_fmac_f32_e32 v63, v40, v40
	v_fmac_f32_e32 v63, v41, v41
	v_fma_f32 v171, v69, v50, 0
	v_fmac_f32_e32 v171, v75, v51
	v_add_f32_dpp v63, v63, v63 quad_perm:[1,0,3,2] row_mask:0xf bank_mask:0xf bound_ctrl:1
	v_fmac_f32_e32 v171, v81, v52
	v_fmac_f32_e32 v171, v87, v53
	v_add_f32_dpp v63, v63, v63 quad_perm:[2,3,0,1] row_mask:0xf bank_mask:0xf bound_ctrl:1
	v_fmac_f32_e32 v171, v93, v46
	v_fmac_f32_e32 v171, v99, v47
	v_add_f32_dpp v63, v63, v63 row_half_mirror row_mask:0xf bank_mask:0xf bound_ctrl:1
	v_fmac_f32_e32 v171, v105, v48
	v_fmac_f32_e32 v171, v111, v49
	v_add_f32_dpp v63, v63, v63 row_mirror row_mask:0xf bank_mask:0xf bound_ctrl:1
	v_mov_b32_e32 v64, v63
	s_nop 1
	v_permlane16_swap_b32_e32 v63, v64
	v_add_f32_e32 v63, v63, v64
	v_mov_b32_e32 v64, v63
	s_nop 1
	v_permlane32_swap_b32_e32 v63, v64
	v_add_f32_e32 v63, v63, v64
	v_fmamk_f32 v63, v63, 0x3a800000, v161
	v_rsq_f32_e32 v64, v63
	v_fma_f32 v63, v65, v50, 0
	v_fmac_f32_e32 v63, v71, v51
	v_fmac_f32_e32 v63, v77, v52
	v_pk_mul_f32 v[164:165], v[50:51], v[64:65] op_sel_hi:[1,0]
	v_pk_mul_f32 v[166:167], v[52:53], v[64:65] op_sel_hi:[1,0]
	v_pk_mul_f32 v[164:165], v[2:3], v[164:165]
	v_pk_mul_f32 v[166:167], v[4:5], v[166:167]
	v_cvt_pk_bf16_f32 v164, v164, v165
	v_cvt_pk_bf16_f32 v165, v166, v167
	v_pk_mul_f32 v[166:167], v[46:47], v[64:65] op_sel_hi:[1,0]
	v_pk_mul_f32 v[168:169], v[48:49], v[64:65] op_sel_hi:[1,0]
	v_pk_mul_f32 v[166:167], v[6:7], v[166:167]
	v_pk_mul_f32 v[168:169], v[8:9], v[168:169]
	v_cvt_pk_bf16_f32 v166, v166, v167
	v_cvt_pk_bf16_f32 v167, v168, v169
	global_store_dwordx4 v[58:59], v[164:167], off
	v_pk_mul_f32 v[168:169], v[40:41], v[64:65] op_sel_hi:[1,0]
	v_fmac_f32_e32 v63, v83, v53
	v_pk_mul_f32 v[164:165], v[42:43], v[64:65] op_sel_hi:[1,0]
	v_pk_mul_f32 v[166:167], v[44:45], v[64:65] op_sel_hi:[1,0]
	v_pk_mul_f32 v[164:165], v[14:15], v[164:165]
	v_pk_mul_f32 v[166:167], v[16:17], v[166:167]
	v_cvt_pk_bf16_f32 v164, v164, v165
	v_cvt_pk_bf16_f32 v165, v166, v167
	v_pk_mul_f32 v[166:167], v[38:39], v[64:65] op_sel_hi:[1,0]
	v_pk_mul_f32 v[168:169], v[12:13], v[168:169]
	v_pk_mul_f32 v[166:167], v[10:11], v[166:167]
	v_fmac_f32_e32 v63, v89, v46
	v_cvt_pk_bf16_f32 v166, v166, v167
	v_cvt_pk_bf16_f32 v167, v168, v169
	global_store_dwordx4 v[58:59], v[164:167], off offset:1024
	v_fma_f32 v169, v68, v50, 0
	v_fmac_f32_e32 v169, v74, v51
	v_fma_f32 v165, v66, v50, 0
	v_fma_f32 v167, v67, v50, 0
	v_fma_f32 v50, v70, v50, 0
	v_fmac_f32_e32 v165, v72, v51
	v_fmac_f32_e32 v167, v73, v51
	v_fmac_f32_e32 v50, v76, v51
	v_fmac_f32_e32 v165, v78, v52
	v_fmac_f32_e32 v167, v79, v52
	v_fmac_f32_e32 v169, v80, v52
	v_fmac_f32_e32 v50, v82, v52
	v_fmac_f32_e32 v165, v84, v53
	v_fmac_f32_e32 v167, v85, v53
	v_fmac_f32_e32 v169, v86, v53
	v_fmac_f32_e32 v50, v88, v53
	v_fmac_f32_e32 v165, v90, v46
	v_fmac_f32_e32 v167, v91, v46
	v_fmac_f32_e32 v169, v92, v46
	v_fmac_f32_e32 v50, v94, v46
	v_fmac_f32_e32 v63, v95, v47
	v_fmac_f32_e32 v165, v96, v47
	v_fmac_f32_e32 v167, v97, v47
	v_fmac_f32_e32 v169, v98, v47
	v_fmac_f32_e32 v50, v100, v47
	v_fmac_f32_e32 v63, v101, v48
	v_fmac_f32_e32 v165, v102, v48
	v_fmac_f32_e32 v167, v103, v48
	v_fmac_f32_e32 v169, v104, v48
	v_fmac_f32_e32 v50, v106, v48
	v_fmac_f32_e32 v63, v107, v49
	v_fmac_f32_e32 v165, v108, v49
	v_fmac_f32_e32 v167, v109, v49
	v_fmac_f32_e32 v169, v110, v49
	v_fmac_f32_e32 v50, v112, v49
	v_fmac_f32_e32 v63, v113, v42
	v_fmac_f32_e32 v165, v114, v42
	v_fmac_f32_e32 v167, v115, v42
	v_fmac_f32_e32 v169, v116, v42
	v_fmac_f32_e32 v171, v117, v42
	v_fmac_f32_e32 v50, v118, v42
	v_fmac_f32_e32 v63, v119, v43
	v_fmac_f32_e32 v165, v120, v43
	v_fmac_f32_e32 v167, v121, v43
	v_fmac_f32_e32 v169, v122, v43
	v_fmac_f32_e32 v171, v123, v43
	v_fmac_f32_e32 v50, v124, v43
	v_fmac_f32_e32 v63, v125, v44
	v_fmac_f32_e32 v165, v126, v44
	v_fmac_f32_e32 v167, v127, v44
	v_fmac_f32_e32 v169, v128, v44
	v_fmac_f32_e32 v171, v129, v44
	v_fmac_f32_e32 v50, v130, v44
	v_fmac_f32_e32 v63, v131, v45
	v_fmac_f32_e32 v165, v132, v45
	v_fmac_f32_e32 v167, v133, v45
	v_fmac_f32_e32 v169, v134, v45
	v_fmac_f32_e32 v171, v135, v45
	v_fmac_f32_e32 v50, v136, v45
	v_fmac_f32_e32 v63, v137, v38
	v_fmac_f32_e32 v165, v138, v38
	v_fmac_f32_e32 v167, v139, v38
	v_fmac_f32_e32 v169, v140, v38
	v_fmac_f32_e32 v171, v141, v38
	v_fmac_f32_e32 v50, v142, v38
	v_fmac_f32_e32 v63, v143, v39
	v_fmac_f32_e32 v165, v144, v39
	v_fmac_f32_e32 v167, v145, v39
	v_fmac_f32_e32 v169, v146, v39
	v_fmac_f32_e32 v171, v147, v39
	v_fmac_f32_e32 v50, v148, v39
	v_fmac_f32_e32 v63, v149, v40
	v_fmac_f32_e32 v165, v150, v40
	v_fmac_f32_e32 v167, v151, v40
	v_fmac_f32_e32 v169, v152, v40
	v_fmac_f32_e32 v171, v153, v40
	v_fmac_f32_e32 v50, v154, v40
	v_fmac_f32_e32 v63, v155, v41
	v_fmac_f32_e32 v165, v156, v41
	v_fmac_f32_e32 v167, v157, v41
	v_fmac_f32_e32 v169, v158, v41
	v_fmac_f32_e32 v171, v159, v41
	v_fmac_f32_e32 v50, v160, v41
	v_add_f32_dpp v63, v63, v63 quad_perm:[1,0,3,2] row_mask:0xf bank_mask:0xf bound_ctrl:1
	v_add_f32_dpp v165, v165, v165 quad_perm:[1,0,3,2] row_mask:0xf bank_mask:0xf bound_ctrl:1
	v_add_f32_dpp v167, v167, v167 quad_perm:[1,0,3,2] row_mask:0xf bank_mask:0xf bound_ctrl:1
; #define DPPF(v, ctrl) __builtin_bit_cast(float, __builtin_amdgcn_update_dpp(0, __builtin_bit_cast(int, (v)), (ctrl), 0xf, 0xf, false))
; __device__ __forceinline__ float xor16_sum(float v) { const auto r = __builtin_amdgcn_permlane16_swap(__float_as_uint(v), __float_as_uint(v), false, false); return __uint_as_float(r[0]) + __uint_as_float(r[1]); }
; __device__ __forceinline__ float xor32_sum(float v) { const auto r = __builtin_amdgcn_permlane32_swap(__float_as_uint(v), __float_as_uint(v), false, false); return __uint_as_float(r[0]) + __uint_as_float(r[1]); }
; __device__ __forceinline__ float row16_sum(float v) { v += DPPF(v, 0xB1); v += DPPF(v, 0x4E); v += DPPF(v, 0x141); v += DPPF(v, 0x140); return v; }
; __device__ __forceinline__ float wave_sum(float v) { return xor32_sum(xor16_sum(row16_sum(v))); }
; template <bool FG, bool BIN = false> __device__ __forceinline__ void norm_phase(const float* hin, const float* gain, bf16_t* out, const float* win, const float* fbias, float* logf, int gw, int NGW, int lane) {
;     ...
;             for (int j = 0; j < 6; ++j) { float d = 0.f;
; #pragma unroll
;                 for (int e = 0; e < 16; ++e) d += x[e] * wf[j][e];
;                 d = wave_sum(d) * rstd + fb[j];
;                 if (lane == j) mine = d; }
	v_add_f32_dpp v169, v169, v169 quad_perm:[1,0,3,2] row_mask:0xf bank_mask:0xf bound_ctrl:1
	v_add_f32_dpp v171, v171, v171 quad_perm:[1,0,3,2] row_mask:0xf bank_mask:0xf bound_ctrl:1
	v_add_f32_dpp v38, v50, v50 quad_perm:[1,0,3,2] row_mask:0xf bank_mask:0xf bound_ctrl:1
	v_add_f32_dpp v63, v63, v63 quad_perm:[2,3,0,1] row_mask:0xf bank_mask:0xf bound_ctrl:1
	v_add_f32_dpp v165, v165, v165 quad_perm:[2,3,0,1] row_mask:0xf bank_mask:0xf bound_ctrl:1
	v_add_f32_dpp v167, v167, v167 quad_perm:[2,3,0,1] row_mask:0xf bank_mask:0xf bound_ctrl:1
	v_add_f32_dpp v169, v169, v169 quad_perm:[2,3,0,1] row_mask:0xf bank_mask:0xf bound_ctrl:1
	v_add_f32_dpp v171, v171, v171 quad_perm:[2,3,0,1] row_mask:0xf bank_mask:0xf bound_ctrl:1
	v_add_f32_dpp v38, v38, v38 quad_perm:[2,3,0,1] row_mask:0xf bank_mask:0xf bound_ctrl:1
	v_add_f32_dpp v63, v63, v63 row_half_mirror row_mask:0xf bank_mask:0xf bound_ctrl:1
	v_add_f32_dpp v165, v165, v165 row_half_mirror row_mask:0xf bank_mask:0xf bound_ctrl:1
	v_add_f32_dpp v167, v167, v167 row_half_mirror row_mask:0xf bank_mask:0xf bound_ctrl:1
	v_add_f32_dpp v169, v169, v169 row_half_mirror row_mask:0xf bank_mask:0xf bound_ctrl:1
	v_add_f32_dpp v171, v171, v171 row_half_mirror row_mask:0xf bank_mask:0xf bound_ctrl:1
	v_add_f32_dpp v38, v38, v38 row_half_mirror row_mask:0xf bank_mask:0xf bound_ctrl:1
	v_add_f32_dpp v63, v63, v63 row_mirror row_mask:0xf bank_mask:0xf bound_ctrl:1
	v_add_f32_dpp v165, v165, v165 row_mirror row_mask:0xf bank_mask:0xf bound_ctrl:1
	v_add_f32_dpp v167, v167, v167 row_mirror row_mask:0xf bank_mask:0xf bound_ctrl:1
	v_add_f32_dpp v169, v169, v169 row_mirror row_mask:0xf bank_mask:0xf bound_ctrl:1
	v_add_f32_dpp v171, v171, v171 row_mirror row_mask:0xf bank_mask:0xf bound_ctrl:1
	v_add_f32_dpp v38, v38, v38 row_mirror row_mask:0xf bank_mask:0xf bound_ctrl:1
	v_mov_b32_e32 v164, v63
	v_mov_b32_e32 v166, v165
	v_mov_b32_e32 v168, v167
	v_mov_b32_e32 v170, v169
	v_mov_b32_e32 v172, v171
	v_mov_b32_e32 v39, v38
	v_permlane16_swap_b32_e32 v63, v164
	v_permlane16_swap_b32_e32 v165, v166
	v_permlane16_swap_b32_e32 v167, v168
	v_permlane16_swap_b32_e32 v169, v170
	v_permlane16_swap_b32_e32 v171, v172
	v_permlane16_swap_b32_e32 v38, v39
	v_add_f32_e32 v63, v63, v164
	v_add_f32_e32 v165, v165, v166
	v_add_f32_e32 v167, v167, v168
	v_add_f32_e32 v169, v169, v170
	v_add_f32_e32 v171, v171, v172
	v_add_f32_e32 v38, v38, v39
	v_mov_b32_e32 v164, v63
	v_mov_b32_e32 v166, v165
	v_mov_b32_e32 v168, v167
	v_mov_b32_e32 v170, v169
	v_mov_b32_e32 v172, v171
	v_mov_b32_e32 v39, v38
	v_permlane32_swap_b32_e32 v63, v164
	v_permlane32_swap_b32_e32 v165, v166
	v_permlane32_swap_b32_e32 v167, v168
	v_permlane32_swap_b32_e32 v169, v170
	v_permlane32_swap_b32_e32 v171, v172
	v_permlane32_swap_b32_e32 v38, v39
	s_and_saveexec_b64 s[0:1], s[4:5]
	s_cbranch_execz .LBB0_169
; __device__ __forceinline__ float wave_sum(float v) { return xor32_sum(xor16_sum(row16_sum(v))); }
; template <bool FG, bool BIN = false> __device__ __forceinline__ void norm_phase(const float* hin, const float* gain, bf16_t* out, const float* win, const float* fbias, float* logf, int gw, int NGW, int lane) {
;     ...
;                 d = wave_sum(d) * rstd + fb[j];
;                 if (lane == j) mine = d; }
;             if (lane < 6) { const float v = mine; logf[(size_t)row * 6 + lane] = fminf(v, 0.f) - log1pf(expf(-fabsf(v))); }
	v_add_f32_e32 v43, v63, v164
	v_add_f32_e32 v42, v165, v166
	v_fma_f32 v43, v64, v43, v18
	v_add_f32_e32 v41, v167, v168
	v_fma_f32 v42, v64, v42, v19
	v_cndmask_b32_e64 v43, 0, v43, s[6:7]
	v_add_f32_e32 v40, v169, v170
	v_fma_f32 v41, v64, v41, v20
	v_cndmask_b32_e64 v42, v43, v42, s[8:9]
	v_add_f32_e32 v38, v38, v39
	v_add_f32_e32 v39, v171, v172
	v_fma_f32 v40, v64, v40, v21
	v_cndmask_b32_e64 v41, v42, v41, s[10:11]
	v_fma_f32 v39, v64, v39, v54
	v_cndmask_b32_e64 v40, v41, v40, s[12:13]
	v_fma_f32 v38, v64, v38, v55
	v_cndmask_b32_e64 v39, v40, v39, s[14:15]
	v_cndmask_b32_e64 v38, v39, v38, s[16:17]
	v_mul_f32_e64 v39, |v38|, s2
	v_fma_f32 v40, |v38|, s2, -v39
	v_rndne_f32_e32 v41, v39
	v_fma_f32 v40, |v38|, s3, v40
	v_sub_f32_e32 v39, v39, v41
	v_add_f32_e32 v39, v39, v40
	v_exp_f32_e32 v39, v39
	v_cvt_i32_f32_e32 v40, v41
	v_cmp_ngt_f32_e64 vcc, |v38|, s21
	v_max_f32_e32 v41, v38, v38
	v_min_f32_e32 v52, 0, v41
	v_ldexp_f32 v39, v39, v40
	v_cndmask_b32_e32 v39, 0, v39, vcc
	v_cmp_nlt_f32_e64 vcc, |v38|, s28
	s_nop 1
	v_cndmask_b32_e32 v53, v163, v39, vcc
	v_add_f32_e32 v40, 1.0, v53
	v_add_f32_e32 v38, -1.0, v40
	v_sub_f32_e32 v39, v38, v40
	v_add_f32_e32 v39, 1.0, v39
	v_sub_f32_e32 v38, v53, v38
	v_add_f32_e32 v41, v38, v39
	v_frexp_mant_f32_e32 v42, v40
	v_cvt_f64_f32_e32 v[38:39], v40
	v_frexp_exp_i32_f64_e32 v38, v[38:39]
	v_cmp_gt_f32_e32 vcc, s30, v42
	s_nop 1
	v_subbrev_co_u32_e32 v46, vcc, 0, v38, vcc
	v_sub_u32_e32 v38, 0, v46
	v_ldexp_f32 v39, v40, v38
	v_add_f32_e32 v40, -1.0, v39
	v_add_f32_e32 v42, 1.0, v39
	v_ldexp_f32 v38, v41, v38
	v_add_f32_e32 v41, 1.0, v40
	v_add_f32_e32 v43, -1.0, v42
	v_sub_f32_e32 v41, v39, v41
	v_sub_f32_e32 v39, v39, v43
	v_add_f32_e32 v41, v38, v41
	v_add_f32_e32 v38, v38, v39
	v_add_f32_e32 v47, v42, v38
	v_rcp_f32_e32 v49, v47
	v_sub_f32_e32 v39, v42, v47
	v_add_f32_e32 v48, v38, v39
	v_add_f32_e32 v39, v40, v41
	v_mul_f32_e32 v51, v39, v49
	v_sub_f32_e32 v38, v40, v39
	v_mul_f32_e32 v40, v47, v51
	v_fma_f32 v42, v51, v47, -v40
	v_fmac_f32_e32 v42, v51, v48
	v_add_f32_e32 v50, v41, v38
	v_add_f32_e32 v38, v40, v42
	v_sub_f32_e32 v41, v39, v38
	v_pk_add_f32 v[44:45], v[38:39], v[40:41] neg_lo:[0,1] neg_hi:[0,1]
	v_mov_b32_e32 v43, v38
	v_pk_add_f32 v[38:39], v[44:45], v[42:43] neg_lo:[0,1] neg_hi:[0,1]
	v_cmp_neq_f32_e32 vcc, s29, v53
	v_add_f32_e32 v39, v50, v39
	v_add_f32_e32 v38, v38, v39
	v_add_f32_e32 v39, v41, v38
	v_mul_f32_e32 v50, v49, v39
	v_mul_f32_e32 v40, v47, v50
	v_fma_f32 v42, v50, v47, -v40
	v_fmac_f32_e32 v42, v50, v48
	v_sub_f32_e32 v41, v41, v39
	v_add_f32_e32 v47, v38, v41
	v_add_f32_e32 v38, v40, v42
	v_sub_f32_e32 v41, v39, v38
	v_pk_add_f32 v[44:45], v[38:39], v[40:41] neg_lo:[0,1] neg_hi:[0,1]
	v_mov_b32_e32 v43, v38
	v_pk_add_f32 v[38:39], v[44:45], v[42:43] neg_lo:[0,1] neg_hi:[0,1]
	s_nop 0
	v_add_f32_e32 v39, v47, v39
	v_add_f32_e32 v38, v38, v39
	v_add_f32_e32 v39, v51, v50
	v_add_f32_e32 v38, v41, v38
	v_sub_f32_e32 v40, v39, v51
	v_mul_f32_e32 v38, v49, v38
	v_sub_f32_e32 v40, v50, v40
	v_add_f32_e32 v40, v40, v38
	v_add_f32_e32 v42, v39, v40
	v_mul_f32_e32 v43, v42, v42
	v_fmamk_f32 v38, v43, 0x3e9b6dac, v162
	v_fmaak_f32 v63, v43, v38, 0x3f2aaada
	v_cvt_f32_i32_e32 v38, v46
	v_sub_f32_e32 v39, v42, v39
	v_sub_f32_e32 v39, v40, v39
	v_ldexp_f32 v44, v39, 1
	v_mul_f32_e32 v39, v42, v43
	v_ldexp_f32 v41, v42, 1
	v_pk_mul_f32 v[42:43], v[38:39], v[62:63]
	s_nop 0
	v_fma_f32 v40, v38, s31, -v42
	v_fmac_f32_e32 v40, 0xb102e308, v38
	v_pk_add_f32 v[38:39], v[42:43], v[40:41]
	s_nop 0
	v_sub_f32_e32 v41, v39, v41
	v_sub_f32_e32 v41, v43, v41
	v_add_f32_e32 v45, v44, v41
	v_mov_b32_e32 v44, v42
	v_pk_add_f32 v[42:43], v[38:39], v[42:43] neg_lo:[0,1] neg_hi:[0,1]
	v_pk_add_f32 v[46:47], v[38:39], v[44:45]
	v_mov_b32_e32 v41, v38
	v_mov_b32_e32 v43, v47
	v_pk_add_f32 v[48:49], v[40:41], v[42:43] neg_lo:[0,1] neg_hi:[0,1]
	v_pk_add_f32 v[40:41], v[40:41], v[42:43]
	v_mov_b32_e32 v44, v45
	v_pk_add_f32 v[42:43], v[40:41], v[38:39] op_sel:[1,0] op_sel_hi:[0,1] neg_lo:[0,1] neg_hi:[0,1]
	v_pk_add_f32 v[50:51], v[46:47], v[42:43] op_sel_hi:[1,0] neg_lo:[0,1] neg_hi:[0,1]
	v_mov_b32_e32 v46, v47
	v_mov_b32_e32 v47, v41
	v_pk_mov_b32 v[42:43], v[38:39], v[42:43] op_sel:[1,0]
	v_mov_b32_e32 v45, v38
	v_pk_add_f32 v[42:43], v[46:47], v[42:43] neg_lo:[0,1] neg_hi:[0,1]
	v_mov_b32_e32 v50, v48
	v_pk_add_f32 v[38:39], v[44:45], v[42:43] neg_lo:[0,1] neg_hi:[0,1]
	v_mov_b32_e32 v49, v41
	v_pk_add_f32 v[42:43], v[50:51], v[38:39]
	s_nop 0
	v_pk_add_f32 v[44:45], v[42:43], v[42:43] op_sel:[0,1] op_sel_hi:[1,0]
	s_nop 0
	v_pk_add_f32 v[40:41], v[40:41], v[44:45] op_sel:[1,0] op_sel_hi:[0,1]
	v_mov_b32_e32 v43, v40
	v_pk_add_f32 v[46:47], v[42:43], v[48:49] neg_lo:[0,1] neg_hi:[0,1]
	v_mov_b32_e32 v39, v44
	v_sub_f32_e32 v41, v42, v46
	v_pk_add_f32 v[38:39], v[38:39], v[46:47] neg_lo:[0,1] neg_hi:[0,1]
	v_sub_f32_e32 v41, v48, v41
	v_add_f32_e32 v38, v38, v41
	v_add_f32_e32 v38, v38, v39
	v_add_f32_e32 v38, v40, v38
	v_cndmask_b32_e32 v38, v163, v38, vcc
	v_cmp_lt_f32_e64 vcc, |v53|, s33
	s_nop 1
	v_cndmask_b32_e32 v38, v38, v53, vcc
	v_sub_f32_e32 v38, v52, v38
	global_store_dword v[56:57], v38, off
	s_branch .LBB0_169
